# FFN-up K-loop: weight-tile LDS-DMA loads marked nt so activations keep L2 residency
# baseline (speedup 1.0000x reference)
.LBB0_944:
	s_add_u32 s2, s66, 0xfffc0080
	s_addc_u32 s14, s67, -1
	s_add_i32 s15, 0, 0x10000
	s_cmp_eq_u32 s42, 12
	s_cselect_b32 s27, s18, s14
	s_cselect_b32 s26, s19, s2
	s_cselect_b32 s25, s8, s68
	s_cselect_b32 s24, s57, s61
	s_add_i32 s2, 0, 0x14000
	v_add_u32_e32 v142, s15, v187
	v_add_u32_e32 v170, s2, v187
	ds_read_b128 v[130:133], v142
	ds_read_b128 v[134:137], v142 offset:1024
	ds_read_b128 v[138:141], v142 offset:2048
	ds_read_b128 v[142:145], v142 offset:3072
	ds_read_b128 v[146:149], v170
	ds_read_b128 v[150:153], v170 offset:1024
	ds_read_b128 v[166:169], v170 offset:2048
	ds_read_b128 v[170:173], v170 offset:3072
	v_lshl_add_u64 v[182:183], s[66:67], 0, v[164:165]
	s_add_i32 m0, s47, 0xc000
	ds_read_b128 v[174:177], v191
	ds_read_b128 v[178:181], v191 offset:1024
	ds_read_b128 v[200:203], v191 offset:2048
	ds_read_b128 v[204:207], v191 offset:3072
	ds_read_b128 v[208:211], v191 offset:4096
	ds_read_b128 v[212:215], v191 offset:5120
	ds_read_b128 v[216:219], v191 offset:6144
	ds_read_b128 v[220:223], v191 offset:7168
	global_load_lds_dwordx4 v[182:183], off
	v_lshl_add_u64 v[182:183], s[66:67], 0, v[162:163]
	s_add_i32 m0, s47, 0xe000
	s_nop 0
	global_load_lds_dwordx4 v[182:183], off
	s_waitcnt vmcnt(8)
	s_waitcnt lgkmcnt(0)
	s_barrier
	s_setprio 1
	s_waitcnt lgkmcnt(0)
	v_mfma_f32_16x16x32_bf16 v[126:129], v[130:133], v[174:177], v[126:129]
	v_mfma_f32_16x16x32_bf16 v[118:121], v[138:141], v[174:177], v[118:121]
	v_mfma_f32_16x16x32_bf16 v[110:113], v[130:133], v[200:203], v[110:113]
	v_mfma_f32_16x16x32_bf16 v[102:105], v[138:141], v[200:203], v[102:105]
	v_mfma_f32_16x16x32_bf16 v[92:95], v[130:133], v[208:211], v[92:95]
	v_mfma_f32_16x16x32_bf16 v[84:87], v[138:141], v[208:211], v[84:87]
	v_mfma_f32_16x16x32_bf16 v[76:79], v[130:133], v[216:219], v[76:79]
	v_mfma_f32_16x16x32_bf16 v[68:71], v[138:141], v[216:219], v[68:71]
	v_mfma_f32_16x16x32_bf16 v[126:129], v[134:137], v[178:181], v[126:129]
	v_mfma_f32_16x16x32_bf16 v[118:121], v[142:145], v[178:181], v[118:121]
	v_mfma_f32_16x16x32_bf16 v[110:113], v[134:137], v[204:207], v[110:113]
	v_mfma_f32_16x16x32_bf16 v[102:105], v[142:145], v[204:207], v[102:105]
	v_mfma_f32_16x16x32_bf16 v[92:95], v[134:137], v[212:215], v[92:95]
	v_mfma_f32_16x16x32_bf16 v[84:87], v[142:145], v[212:215], v[84:87]
	v_mfma_f32_16x16x32_bf16 v[76:79], v[134:137], v[220:223], v[76:79]
	v_mfma_f32_16x16x32_bf16 v[68:71], v[142:145], v[220:223], v[68:71]
	s_setprio 0
	s_setprio 1
	v_mfma_f32_16x16x32_bf16 v[122:125], v[146:149], v[174:177], v[122:125]
	v_mfma_f32_16x16x32_bf16 v[114:117], v[166:169], v[174:177], v[114:117]
	v_mfma_f32_16x16x32_bf16 v[106:109], v[146:149], v[200:203], v[106:109]
	v_mfma_f32_16x16x32_bf16 v[98:101], v[166:169], v[200:203], v[98:101]
	v_mfma_f32_16x16x32_bf16 v[88:91], v[146:149], v[208:211], v[88:91]
	v_mfma_f32_16x16x32_bf16 v[80:83], v[166:169], v[208:211], v[80:83]
	v_mfma_f32_16x16x32_bf16 v[72:75], v[146:149], v[216:219], v[72:75]
	v_mfma_f32_16x16x32_bf16 v[64:67], v[166:169], v[216:219], v[64:67]
	v_mfma_f32_16x16x32_bf16 v[122:125], v[150:153], v[178:181], v[122:125]
	v_mfma_f32_16x16x32_bf16 v[114:117], v[170:173], v[178:181], v[114:117]
	v_mfma_f32_16x16x32_bf16 v[106:109], v[150:153], v[204:207], v[106:109]
	v_mfma_f32_16x16x32_bf16 v[98:101], v[170:173], v[204:207], v[98:101]
	v_mfma_f32_16x16x32_bf16 v[88:91], v[150:153], v[212:215], v[88:91]
	v_mfma_f32_16x16x32_bf16 v[80:83], v[170:173], v[212:215], v[80:83]
	v_mfma_f32_16x16x32_bf16 v[72:75], v[150:153], v[220:223], v[72:75]
	v_mfma_f32_16x16x32_bf16 v[64:67], v[170:173], v[220:223], v[64:67]
	s_setprio 0
	s_barrier
	s_add_i32 s14, s15, s39
	v_lshl_add_u64 v[182:183], s[24:25], 0, v[96:97]
	s_mov_b32 m0, s14
	ds_read_b128 v[174:177], v191 offset:16384
	ds_read_b128 v[178:181], v191 offset:17408
	ds_read_b128 v[200:203], v191 offset:18432
	ds_read_b128 v[204:207], v191 offset:19456
	ds_read_b128 v[208:211], v191 offset:20480
	ds_read_b128 v[212:215], v191 offset:21504
	ds_read_b128 v[216:219], v191 offset:22528
	ds_read_b128 v[220:223], v191 offset:23552
	global_load_lds_dwordx4 v[182:183], off nt
	s_add_i32 m0, s14, 0x2000
	s_add_u32 s14, s24, 0x40000
	v_lshl_add_u64 v[188:189], s[24:25], 0, v[154:155]
	s_addc_u32 s15, s25, 0
	s_add_i32 s2, s2, s39
	global_load_lds_dwordx4 v[188:189], off nt
	v_lshl_add_u64 v[192:193], s[14:15], 0, v[96:97]
	s_mov_b32 m0, s2
	v_lshl_add_u64 v[224:225], s[26:27], 0, v[156:157]
	global_load_lds_dwordx4 v[192:193], off nt
	v_lshl_add_u64 v[192:193], s[14:15], 0, v[154:155]
	s_add_i32 m0, s2, 0x2000
	s_nop 0
	global_load_lds_dwordx4 v[192:193], off nt
	v_lshl_add_u64 v[192:193], s[26:27], 0, v[158:159]
	s_mov_b32 m0, s47
	s_nop 0
	global_load_lds_dwordx4 v[192:193], off
	s_mov_b32 m0, s70
	s_nop 0
	global_load_lds_dwordx4 v[224:225], off
	s_waitcnt vmcnt(8)
	s_waitcnt lgkmcnt(0)
	s_barrier
	s_setprio 1
	s_waitcnt lgkmcnt(0)
	v_mfma_f32_16x16x32_bf16 v[60:63], v[130:133], v[174:177], v[60:63]
	v_mfma_f32_16x16x32_bf16 v[52:55], v[138:141], v[174:177], v[52:55]
	v_mfma_f32_16x16x32_bf16 v[44:47], v[130:133], v[200:203], v[44:47]
	v_mfma_f32_16x16x32_bf16 v[36:39], v[138:141], v[200:203], v[36:39]
	v_mfma_f32_16x16x32_bf16 v[28:31], v[130:133], v[208:211], v[28:31]
	v_mfma_f32_16x16x32_bf16 v[20:23], v[138:141], v[208:211], v[20:23]
	v_mfma_f32_16x16x32_bf16 v[12:15], v[130:133], v[216:219], v[12:15]
	v_mfma_f32_16x16x32_bf16 v[4:7], v[138:141], v[216:219], v[4:7]
	v_mfma_f32_16x16x32_bf16 v[60:63], v[134:137], v[178:181], v[60:63]
	v_mfma_f32_16x16x32_bf16 v[52:55], v[142:145], v[178:181], v[52:55]
	v_mfma_f32_16x16x32_bf16 v[44:47], v[134:137], v[204:207], v[44:47]
	v_mfma_f32_16x16x32_bf16 v[36:39], v[142:145], v[204:207], v[36:39]
	v_mfma_f32_16x16x32_bf16 v[28:31], v[134:137], v[212:215], v[28:31]
	v_mfma_f32_16x16x32_bf16 v[20:23], v[142:145], v[212:215], v[20:23]
	v_mfma_f32_16x16x32_bf16 v[12:15], v[134:137], v[220:223], v[12:15]
	v_mfma_f32_16x16x32_bf16 v[4:7], v[142:145], v[220:223], v[4:7]
	s_setprio 0
	s_setprio 1
	v_mfma_f32_16x16x32_bf16 v[56:59], v[146:149], v[174:177], v[56:59]
	v_mfma_f32_16x16x32_bf16 v[48:51], v[166:169], v[174:177], v[48:51]
	v_mfma_f32_16x16x32_bf16 v[40:43], v[146:149], v[200:203], v[40:43]
	v_mfma_f32_16x16x32_bf16 v[32:35], v[166:169], v[200:203], v[32:35]
	v_mfma_f32_16x16x32_bf16 v[24:27], v[146:149], v[208:211], v[24:27]
	v_mfma_f32_16x16x32_bf16 v[16:19], v[166:169], v[208:211], v[16:19]
	v_mfma_f32_16x16x32_bf16 v[8:11], v[146:149], v[216:219], v[8:11]
	v_mfma_f32_16x16x32_bf16 v[0:3], v[166:169], v[216:219], v[0:3]
	v_mfma_f32_16x16x32_bf16 v[56:59], v[150:153], v[178:181], v[56:59]
	v_mfma_f32_16x16x32_bf16 v[48:51], v[170:173], v[178:181], v[48:51]
	v_mfma_f32_16x16x32_bf16 v[40:43], v[150:153], v[204:207], v[40:43]
	v_mfma_f32_16x16x32_bf16 v[32:35], v[170:173], v[204:207], v[32:35]
	v_mfma_f32_16x16x32_bf16 v[24:27], v[150:153], v[212:215], v[24:27]
	v_mfma_f32_16x16x32_bf16 v[16:19], v[170:173], v[212:215], v[16:19]
	v_mfma_f32_16x16x32_bf16 v[8:11], v[150:153], v[220:223], v[8:11]
	v_mfma_f32_16x16x32_bf16 v[0:3], v[170:173], v[220:223], v[0:3]
	s_setprio 0
	s_barrier
	s_add_i32 s2, 0, 0x18000
	s_add_i32 s20, 0, 0x1c000
	v_add_u32_e32 v142, s2, v187
	v_add_u32_e32 v170, s20, v187
	ds_read_b128 v[130:133], v142
	ds_read_b128 v[134:137], v142 offset:1024
	ds_read_b128 v[138:141], v142 offset:2048
	ds_read_b128 v[142:145], v142 offset:3072
	ds_read_b128 v[146:149], v170
	ds_read_b128 v[150:153], v170 offset:1024
	ds_read_b128 v[166:169], v170 offset:2048
	ds_read_b128 v[170:173], v170 offset:3072
	s_add_u32 s14, s26, 0x40000
	s_addc_u32 s15, s27, 0
	s_mov_b32 m0, s71
	v_lshl_add_u64 v[226:227], s[14:15], 0, v[158:159]
	ds_read_b128 v[174:177], v191 offset:32768
	ds_read_b128 v[178:181], v191 offset:33792
	ds_read_b128 v[200:203], v191 offset:34816
	ds_read_b128 v[204:207], v191 offset:35840
	ds_read_b128 v[208:211], v191 offset:36864
	ds_read_b128 v[212:215], v191 offset:37888
	ds_read_b128 v[216:219], v191 offset:38912
	ds_read_b128 v[220:223], v191 offset:39936
	global_load_lds_dwordx4 v[226:227], off
	v_lshl_add_u64 v[226:227], s[14:15], 0, v[156:157]
	s_mov_b32 m0, s72
	s_nop 0
	global_load_lds_dwordx4 v[226:227], off
	s_waitcnt vmcnt(8)
	s_waitcnt lgkmcnt(0)
	s_barrier
	s_setprio 1
	s_waitcnt lgkmcnt(0)
	v_mfma_f32_16x16x32_bf16 v[126:129], v[130:133], v[174:177], v[126:129]
	v_mfma_f32_16x16x32_bf16 v[118:121], v[138:141], v[174:177], v[118:121]
	v_mfma_f32_16x16x32_bf16 v[110:113], v[130:133], v[200:203], v[110:113]
	v_mfma_f32_16x16x32_bf16 v[102:105], v[138:141], v[200:203], v[102:105]
	v_mfma_f32_16x16x32_bf16 v[92:95], v[130:133], v[208:211], v[92:95]
	v_mfma_f32_16x16x32_bf16 v[84:87], v[138:141], v[208:211], v[84:87]
	v_mfma_f32_16x16x32_bf16 v[76:79], v[130:133], v[216:219], v[76:79]
	v_mfma_f32_16x16x32_bf16 v[68:71], v[138:141], v[216:219], v[68:71]
	v_mfma_f32_16x16x32_bf16 v[126:129], v[134:137], v[178:181], v[126:129]
	v_mfma_f32_16x16x32_bf16 v[118:121], v[142:145], v[178:181], v[118:121]
	v_mfma_f32_16x16x32_bf16 v[110:113], v[134:137], v[204:207], v[110:113]
	v_mfma_f32_16x16x32_bf16 v[102:105], v[142:145], v[204:207], v[102:105]
	v_mfma_f32_16x16x32_bf16 v[92:95], v[134:137], v[212:215], v[92:95]
	v_mfma_f32_16x16x32_bf16 v[84:87], v[142:145], v[212:215], v[84:87]
	v_mfma_f32_16x16x32_bf16 v[76:79], v[134:137], v[220:223], v[76:79]
	v_mfma_f32_16x16x32_bf16 v[68:71], v[142:145], v[220:223], v[68:71]
	s_setprio 0
	s_setprio 1
	v_mfma_f32_16x16x32_bf16 v[122:125], v[146:149], v[174:177], v[122:125]
	v_mfma_f32_16x16x32_bf16 v[114:117], v[166:169], v[174:177], v[114:117]
	v_mfma_f32_16x16x32_bf16 v[106:109], v[146:149], v[200:203], v[106:109]
	v_mfma_f32_16x16x32_bf16 v[98:101], v[166:169], v[200:203], v[98:101]
	v_mfma_f32_16x16x32_bf16 v[88:91], v[146:149], v[208:211], v[88:91]
	v_mfma_f32_16x16x32_bf16 v[80:83], v[166:169], v[208:211], v[80:83]
	v_mfma_f32_16x16x32_bf16 v[72:75], v[146:149], v[216:219], v[72:75]
	v_mfma_f32_16x16x32_bf16 v[64:67], v[166:169], v[216:219], v[64:67]
	v_mfma_f32_16x16x32_bf16 v[122:125], v[150:153], v[178:181], v[122:125]
	v_mfma_f32_16x16x32_bf16 v[114:117], v[170:173], v[178:181], v[114:117]
	v_mfma_f32_16x16x32_bf16 v[106:109], v[150:153], v[204:207], v[106:109]
	v_mfma_f32_16x16x32_bf16 v[98:101], v[170:173], v[204:207], v[98:101]
	v_mfma_f32_16x16x32_bf16 v[88:91], v[150:153], v[212:215], v[88:91]
	v_mfma_f32_16x16x32_bf16 v[80:83], v[170:173], v[212:215], v[80:83]
	v_mfma_f32_16x16x32_bf16 v[72:75], v[150:153], v[220:223], v[72:75]
	v_mfma_f32_16x16x32_bf16 v[64:67], v[170:173], v[220:223], v[64:67]
	s_setprio 0
	s_barrier
	s_add_i32 s2, s2, s39
	v_lshl_add_u64 v[182:183], v[182:183], 0, s[22:23]
	s_mov_b32 m0, s2
	ds_read_b128 v[174:177], v191 offset:49152
	ds_read_b128 v[178:181], v191 offset:50176
	ds_read_b128 v[200:203], v191 offset:51200
	ds_read_b128 v[204:207], v191 offset:52224
	ds_read_b128 v[208:211], v191 offset:53248
	ds_read_b128 v[212:215], v191 offset:54272
	ds_read_b128 v[216:219], v191 offset:55296
	ds_read_b128 v[220:223], v191 offset:56320
	global_load_lds_dwordx4 v[182:183], off nt
	s_add_i32 m0, s2, 0x2000
	s_add_u32 s14, s24, 0x40080
	v_lshl_add_u64 v[182:183], v[188:189], 0, s[22:23]
	s_addc_u32 s15, s25, 0
	s_add_i32 s2, s20, s39
	global_load_lds_dwordx4 v[182:183], off nt
	v_lshl_add_u64 v[182:183], s[14:15], 0, v[96:97]
	s_mov_b32 m0, s2
	s_nop 0
	global_load_lds_dwordx4 v[182:183], off nt
	v_lshl_add_u64 v[182:183], s[14:15], 0, v[154:155]
	s_add_i32 m0, s2, 0x2000
	s_nop 0
	global_load_lds_dwordx4 v[182:183], off nt
	v_lshl_add_u64 v[182:183], v[192:193], 0, s[22:23]
	s_mov_b32 m0, s73
	s_nop 0
	global_load_lds_dwordx4 v[182:183], off
	v_lshl_add_u64 v[182:183], v[224:225], 0, s[22:23]
	s_mov_b32 m0, s74
	s_nop 0
	global_load_lds_dwordx4 v[182:183], off
	s_waitcnt vmcnt(8)
	s_waitcnt lgkmcnt(0)
	s_barrier
	s_setprio 1
	s_waitcnt lgkmcnt(0)
	v_mfma_f32_16x16x32_bf16 v[60:63], v[130:133], v[174:177], v[60:63]
	v_mfma_f32_16x16x32_bf16 v[52:55], v[138:141], v[174:177], v[52:55]
	v_mfma_f32_16x16x32_bf16 v[44:47], v[130:133], v[200:203], v[44:47]
	v_mfma_f32_16x16x32_bf16 v[36:39], v[138:141], v[200:203], v[36:39]
	v_mfma_f32_16x16x32_bf16 v[28:31], v[130:133], v[208:211], v[28:31]
	v_mfma_f32_16x16x32_bf16 v[20:23], v[138:141], v[208:211], v[20:23]
	v_mfma_f32_16x16x32_bf16 v[12:15], v[130:133], v[216:219], v[12:15]
	v_mfma_f32_16x16x32_bf16 v[4:7], v[138:141], v[216:219], v[4:7]
	v_mfma_f32_16x16x32_bf16 v[60:63], v[134:137], v[178:181], v[60:63]
	v_mfma_f32_16x16x32_bf16 v[52:55], v[142:145], v[178:181], v[52:55]
	v_mfma_f32_16x16x32_bf16 v[44:47], v[134:137], v[204:207], v[44:47]
	v_mfma_f32_16x16x32_bf16 v[36:39], v[142:145], v[204:207], v[36:39]
	v_mfma_f32_16x16x32_bf16 v[28:31], v[134:137], v[212:215], v[28:31]
	v_mfma_f32_16x16x32_bf16 v[20:23], v[142:145], v[212:215], v[20:23]
	v_mfma_f32_16x16x32_bf16 v[12:15], v[134:137], v[220:223], v[12:15]
	v_mfma_f32_16x16x32_bf16 v[4:7], v[142:145], v[220:223], v[4:7]
	s_setprio 0
	s_setprio 1
	v_mfma_f32_16x16x32_bf16 v[56:59], v[146:149], v[174:177], v[56:59]
	v_mfma_f32_16x16x32_bf16 v[48:51], v[166:169], v[174:177], v[48:51]
	v_mfma_f32_16x16x32_bf16 v[40:43], v[146:149], v[200:203], v[40:43]
	v_mfma_f32_16x16x32_bf16 v[32:35], v[166:169], v[200:203], v[32:35]
	v_mfma_f32_16x16x32_bf16 v[24:27], v[146:149], v[208:211], v[24:27]
	v_mfma_f32_16x16x32_bf16 v[16:19], v[166:169], v[208:211], v[16:19]
	v_mfma_f32_16x16x32_bf16 v[8:11], v[146:149], v[216:219], v[8:11]
	v_mfma_f32_16x16x32_bf16 v[0:3], v[166:169], v[216:219], v[0:3]
	v_mfma_f32_16x16x32_bf16 v[56:59], v[150:153], v[178:181], v[56:59]
	v_mfma_f32_16x16x32_bf16 v[48:51], v[170:173], v[178:181], v[48:51]
	v_mfma_f32_16x16x32_bf16 v[40:43], v[150:153], v[204:207], v[40:43]
	v_mfma_f32_16x16x32_bf16 v[32:35], v[170:173], v[204:207], v[32:35]
	v_mfma_f32_16x16x32_bf16 v[24:27], v[150:153], v[212:215], v[24:27]
	v_mfma_f32_16x16x32_bf16 v[16:19], v[170:173], v[212:215], v[16:19]
	v_mfma_f32_16x16x32_bf16 v[8:11], v[150:153], v[220:223], v[8:11]
	v_mfma_f32_16x16x32_bf16 v[0:3], v[170:173], v[220:223], v[0:3]
	s_setprio 0
	s_barrier
	s_add_i32 s42, s42, 2
	s_add_u32 s61, s61, 0x100
	s_addc_u32 s68, s68, 0
	s_add_u32 s66, s66, 0x100
	s_addc_u32 s67, s67, 0
	s_cmp_gt_u32 s42, 13
	s_cbranch_scc0 .LBB0_944
	v_lshl_add_u32 v180, s4, 8, v185
	v_lshl_add_u32 v199, s60, 8, v185
	v_mov_b32_e32 v251, 0
	v_lshlrev_b32_e32 v250, 6, v199
	v_lshl_add_u64 v[194:195], v[160:161], 0, v[250:251]
	global_load_dwordx4 v[200:203], v[194:195], off
	v_add_u32_e32 v250, 0x10, v199
	v_lshlrev_b32_e32 v250, 6, v250
	v_lshl_add_u64 v[194:195], v[160:161], 0, v[250:251]
	global_load_dwordx4 v[204:207], v[194:195], off
	v_add_u32_e32 v250, 0x20, v199
	v_lshlrev_b32_e32 v250, 6, v250
	v_lshl_add_u64 v[194:195], v[160:161], 0, v[250:251]
	global_load_dwordx4 v[150:153], v[194:195], off
	v_add_u32_e32 v250, 0x30, v199
	v_lshlrev_b32_e32 v250, 6, v250
	v_lshl_add_u64 v[194:195], v[160:161], 0, v[250:251]
	global_load_dwordx4 v[146:149], v[194:195], off
	v_add_u32_e32 v250, 0x80, v199
	v_lshlrev_b32_e32 v250, 6, v250
	v_lshl_add_u64 v[194:195], v[160:161], 0, v[250:251]
	global_load_dwordx4 v[142:145], v[194:195], off
	v_add_u32_e32 v250, 0x90, v199
	v_lshlrev_b32_e32 v250, 6, v250
	v_lshl_add_u64 v[194:195], v[160:161], 0, v[250:251]
	global_load_dwordx4 v[138:141], v[194:195], off
	v_add_u32_e32 v250, 0xa0, v199
	v_lshlrev_b32_e32 v250, 6, v250
	v_lshl_add_u64 v[194:195], v[160:161], 0, v[250:251]
	global_load_dwordx4 v[134:137], v[194:195], off
	v_add_u32_e32 v250, 0xb0, v199
	v_lshlrev_b32_e32 v250, 6, v250
	v_lshl_add_u64 v[194:195], v[160:161], 0, v[250:251]
	global_load_dwordx4 v[130:133], v[194:195], off
	v_or_b32_e32 v178, 16, v180
	v_or_b32_e32 v176, 32, v180
	v_or_b32_e32 v174, 48, v180
	v_add_u32_e32 v172, 0x80, v180
	v_add_u32_e32 v170, 0x90, v180
	v_add_u32_e32 v168, 0xa0, v180
	v_add_u32_e32 v166, 0xb0, v180
	s_and_b64 vcc, exec, s[58:59]
	s_cbranch_vccz .LBB0_947
	s_barrier
